# v117 stack plus the same x-load hoist in the norm1 (half 0) code copy
# baseline (speedup 1.0000x reference)
.LBB0_1123:
	s_or_b64 exec, exec, s[20:21]
	v_add_u32_e32 v4, 16, v4
	v_and_b32_e32 v1, v5, v16
	v_ashrrev_i32_e32 v5, 31, v4
	v_lshlrev_b32_e32 v176, 12, v1
	v_lshlrev_b64 v[0:1], v0, v[4:5]
	v_lshl_add_u64 v[0:1], v[2:3], 0, v[0:1]
	v_lshl_add_u64 v[0:1], v[0:1], 0, v[176:177]
	v_readlane_b32 s0, v253, 0
	v_mov_b32_e32 v23, v177
	v_readlane_b32 s1, v253, 1
	v_lshl_add_u64 v[0:1], v[0:1], 0, v[22:23]
	s_load_dwordx16 s[4:19], s[0:1], 0xf0
	global_load_dwordx4 v[12:15], v[0:1], off nt
	global_load_dwordx4 v[8:11], v[0:1], off offset:16 nt
	global_load_dwordx4 v[64:67], v[0:1], off offset:2048 nt
	global_load_dwordx4 v[68:71], v[0:1], off offset:2064 nt
	v_cndmask_b32_e64 v7, v5, 0, vcc
	v_cndmask_b32_e64 v6, v4, 32, vcc
	v_lshl_add_u64 v[2:3], v[6:7], 0, s[48:49]
	s_waitcnt lgkmcnt(0)
	v_mov_b64_e32 v[4:5], s[6:7]
	s_movk_i32 s4, 0x6000
	v_mad_u64_u32 v[28:29], s[0:1], v2, s4, v[4:5]
	v_mov_b32_e32 v2, v29
	v_mad_u64_u32 v[2:3], s[0:1], v3, s4, v[2:3]
	v_mov_b32_e32 v29, v2
	s_mov_b32 s0, 0x800000
	v_add_u32_e32 v16, s68, v16
	s_movk_i32 s92, 0x6000
	s_waitcnt vmcnt(2)
	v_mov_b32_e32 v4, v13
	v_mov_b32_e32 v5, v9
	v_mov_b32_e32 v2, v12
	v_mov_b32_e32 v3, v8
	v_pk_mul_f32 v[4:5], v[4:5], v[4:5]
	s_nop 0
	v_pk_fma_f32 v[2:3], v[2:3], v[2:3], v[4:5]
	v_mov_b32_e32 v4, v14
	v_mov_b32_e32 v5, v10
	v_pk_fma_f32 v[2:3], v[4:5], v[4:5], v[2:3]
	v_mov_b32_e32 v4, v15
	v_mov_b32_e32 v5, v11
	v_pk_fma_f32 v[30:31], v[4:5], v[4:5], v[2:3]
	s_waitcnt vmcnt(1)
	v_mov_b32_e32 v4, v64
	v_mov_b32_e32 v5, v65
	v_mov_b32_e32 v6, v66
	v_mov_b32_e32 v7, v67
	s_waitcnt vmcnt(0)
	v_mov_b32_e32 v0, v68
	v_mov_b32_e32 v1, v69
	v_mov_b32_e32 v2, v70
	v_mov_b32_e32 v3, v71
	v_add_f32_e32 v17, v30, v31
	s_waitcnt vmcnt(1)
	v_mov_b32_e32 v40, v5
	s_waitcnt vmcnt(0)
	v_mov_b32_e32 v41, v1
	v_mov_b32_e32 v38, v4
	v_mov_b32_e32 v39, v0
	v_pk_mul_f32 v[40:41], v[40:41], v[40:41]
	s_nop 0
	v_pk_fma_f32 v[38:39], v[38:39], v[38:39], v[40:41]
	v_mov_b32_e32 v40, v6
	v_mov_b32_e32 v41, v2
	v_pk_fma_f32 v[38:39], v[40:41], v[40:41], v[38:39]
	v_mov_b32_e32 v40, v7
	v_mov_b32_e32 v41, v3
	v_pk_fma_f32 v[38:39], v[40:41], v[40:41], v[38:39]
	s_nop 0
	v_add_f32_e32 v17, v17, v38
	v_add_f32_e32 v17, v17, v39
	ds_bpermute_b32 v25, v27, v17
	s_waitcnt lgkmcnt(0)
	v_add_f32_e32 v17, v17, v25
	ds_bpermute_b32 v25, v32, v17
	s_waitcnt lgkmcnt(0)
	v_add_f32_e32 v17, v17, v25
	ds_bpermute_b32 v25, v33, v17
	s_waitcnt lgkmcnt(0)
	v_add_f32_e32 v17, v17, v25
	ds_bpermute_b32 v25, v34, v17
	s_waitcnt lgkmcnt(0)
	v_add_f32_e32 v17, v17, v25
	ds_bpermute_b32 v25, v35, v17
	s_waitcnt lgkmcnt(0)
	v_add_f32_e32 v17, v17, v25
	ds_bpermute_b32 v25, v36, v17
	s_waitcnt lgkmcnt(0)
	v_add_f32_e32 v17, v17, v25
	v_fmamk_f32 v17, v17, 0x3a800000, v194
	v_cmp_gt_f32_e32 vcc, s0, v17
	s_mov_b64 s[0:1], 0x1000
	v_lshl_add_u64 v[30:31], v[28:29], 0, s[0:1]
	v_lshl_add_u64 v[28:29], v[28:29], 0, v[22:23]
	v_lshl_add_u64 v[50:51], v[30:31], 0, v[22:23]
	global_load_dwordx4 v[38:41], v[28:29], off offset:16
	global_load_dwordx4 v[42:45], v[28:29], off
	global_load_dwordx4 v[46:49], v[50:51], off offset:16
	s_nop 0
	global_load_dwordx4 v[50:53], v[50:51], off
	v_mul_f32_e32 v25, 0x4b800000, v17
	v_cndmask_b32_e32 v17, v17, v25, vcc
	v_rsq_f32_e32 v17, v17
	v_readlane_b32 s0, v254, 14
	v_readlane_b32 s1, v254, 15
	v_mul_f32_e32 v25, 0x45800000, v17
	v_cndmask_b32_e32 v26, v17, v25, vcc
	v_pk_mul_f32 v[14:15], v[14:15], v[26:27] op_sel_hi:[1,0]
	v_pk_mul_f32 v[12:13], v[12:13], v[26:27] op_sel_hi:[1,0]
	v_pk_mul_f32 v[8:9], v[8:9], v[26:27] op_sel_hi:[1,0]
	v_pk_mul_f32 v[10:11], v[10:11], v[26:27] op_sel_hi:[1,0]
	v_mov_b32_e32 v25, v177
	v_pk_mul_f32 v[6:7], v[6:7], v[26:27] op_sel_hi:[1,0]
	v_pk_mul_f32 v[4:5], v[4:5], v[26:27] op_sel_hi:[1,0]
	v_pk_mul_f32 v[0:1], v[0:1], v[26:27] op_sel_hi:[1,0]
	v_pk_mul_f32 v[2:3], v[2:3], v[26:27] op_sel_hi:[1,0]
	s_waitcnt vmcnt(0)
	v_pk_add_f32 v[60:61], v[52:53], 1.0 op_sel_hi:[1,0]
	global_load_dwordx4 v[52:55], v[18:19], off offset:16
	global_load_dwordx4 v[56:59], v[18:19], off
	s_waitcnt vmcnt(1)
	v_pk_mul_f32 v[8:9], v[8:9], v[52:53]
	s_waitcnt vmcnt(0)
	v_pk_mul_f32 v[14:15], v[58:59], v[14:15]
	v_pk_mul_f32 v[12:13], v[56:57], v[12:13]
	v_pk_fma_f32 v[14:15], v[60:61], v[14:15], v[44:45]
	v_pk_add_f32 v[44:45], v[50:51], 1.0 op_sel_hi:[1,0]
	v_pk_mul_f32 v[10:11], v[10:11], v[54:55]
	v_pk_fma_f32 v[12:13], v[44:45], v[12:13], v[42:43]
	s_nop 0
	v_cvt_pk_bf16_f32 v12, v12, v13
	v_cvt_pk_bf16_f32 v13, v14, v15
	v_pk_add_f32 v[14:15], v[46:47], 1.0 op_sel_hi:[1,0]
	s_nop 0
	v_pk_fma_f32 v[8:9], v[14:15], v[8:9], v[38:39]
	v_lshl_add_u64 v[38:39], v[30:31], 0, v[24:25]
	v_cvt_pk_bf16_f32 v14, v8, v9
	v_pk_add_f32 v[8:9], v[48:49], 1.0 op_sel_hi:[1,0]
	s_nop 0
	v_pk_fma_f32 v[8:9], v[8:9], v[10:11], v[40:41]
	s_nop 0
	v_cvt_pk_bf16_f32 v15, v8, v9
	global_store_dwordx4 v[20:21], v[12:15], off offset:-1024
	global_load_dwordx4 v[8:11], v[28:29], off offset:2064
	s_nop 0
	global_load_dwordx4 v[12:15], v[28:29], off offset:2048
	s_nop 0
	global_load_dwordx4 v[28:31], v[38:39], off offset:16
	s_nop 0
	global_load_dwordx4 v[38:41], v[38:39], off
	s_waitcnt vmcnt(0)
	v_pk_add_f32 v[48:49], v[40:41], 1.0 op_sel_hi:[1,0]
	global_load_dwordx4 v[40:43], v[18:19], off offset:2064
	global_load_dwordx4 v[44:47], v[18:19], off offset:2048
	s_waitcnt vmcnt(1)
	v_pk_mul_f32 v[0:1], v[0:1], v[40:41]
	s_waitcnt vmcnt(0)
	v_pk_mul_f32 v[6:7], v[6:7], v[46:47]
	v_pk_mul_f32 v[4:5], v[4:5], v[44:45]
	v_pk_fma_f32 v[6:7], v[48:49], v[6:7], v[14:15]
	v_pk_add_f32 v[14:15], v[38:39], 1.0 op_sel_hi:[1,0]
	v_pk_mul_f32 v[2:3], v[2:3], v[42:43]
	v_pk_fma_f32 v[4:5], v[14:15], v[4:5], v[12:13]
	s_nop 0
	v_cvt_pk_bf16_f32 v4, v4, v5
	v_cvt_pk_bf16_f32 v5, v6, v7
	v_pk_add_f32 v[6:7], v[28:29], 1.0 op_sel_hi:[1,0]
	s_nop 0
	v_pk_fma_f32 v[0:1], v[6:7], v[0:1], v[8:9]
	s_nop 0
	v_cvt_pk_bf16_f32 v6, v0, v1
	v_pk_add_f32 v[0:1], v[30:31], 1.0 op_sel_hi:[1,0]
	s_nop 0
	v_pk_fma_f32 v[0:1], v[0:1], v[2:3], v[10:11]
	s_nop 0
	v_cvt_pk_bf16_f32 v7, v0, v1
	global_store_dwordx4 v[20:21], v[4:7], off
	v_lshl_add_u64 v[20:21], v[20:21], 0, s[0:1]
	s_mov_b32 s0, 0x8fff
	v_cmp_lt_i32_e32 vcc, s0, v16
	s_or_b64 s[50:51], vcc, s[50:51]
	s_andn2_b64 exec, exec, s[50:51]
	s_cbranch_execz .LBB0_1128
